# SWA sink logit loaded at the start of the softmax section instead of after PV
# speedup vs baseline: 1.0105x; 1.0065x over previous
.LBB0_1133:
	v_readlane_b32 s100, v252, 18
	v_readlane_b32 s101, v252, 19
	v_bfe_u32 v241, v99, 5, 3
	v_or_b32_e32 v241, s90, v241
	v_lshlrev_b32_e32 v241, 2, v241
	s_nop 3
	global_load_dword v241, v241, s[100:101]
	v_ashrrev_i32_e32 v98, 9, v99
	v_cmp_eq_u32_e32 vcc, 2, v98
	s_mov_b32 s10, 0xff800000
	s_nop 0
	v_cndmask_b32_e64 v0, 0, 4, vcc
	v_cmp_ne_u32_e32 vcc, 1, v98
	s_nop 1
	v_cndmask_b32_e32 v0, 2, v0, vcc
	v_lshrrev_b32_e64 v2, v0, 32
	v_add_u32_e32 v2, -1, v2
	v_bitop3_b32 v2, v2, v99, 31 bitop3:0x80
	v_cmp_eq_u32_e32 vcc, 3, v98
	v_lshlrev_b32_e32 v3, 7, v2
	v_sub_u32_e32 v2, 0x7f, v3
	v_cndmask_b32_e32 v97, v229, v230, vcc
	s_nop 0
	v_readfirstlane_b32 s100, v2
	s_nop 1
	s_cmp_lt_i32 s100, 0
	s_cbranch_scc0 .Lattn_mask_full
	v_cmp_le_u32_e64 s[46:47], v116, v97
	v_cmp_le_u32_e64 s[34:35], v117, v97
	v_cmp_le_u32_e64 s[100:101], v119, v97
	v_cmp_le_u32_e32 vcc, v121, v97
	v_cndmask_b32_e64 v56, v231, v56, s[46:47]
	v_cndmask_b32_e64 v57, v231, v57, s[34:35]
	v_cndmask_b32_e64 v58, v231, v58, s[100:101]
	v_cndmask_b32_e32 v59, v231, v59, vcc
	v_cmp_le_u32_e64 s[46:47], v123, v97
	v_cmp_le_u32_e64 s[34:35], v124, v97
	v_cmp_le_u32_e64 s[100:101], v126, v97
	v_cmp_le_u32_e32 vcc, v128, v97
	v_cndmask_b32_e64 v72, v231, v72, s[46:47]
	v_cndmask_b32_e64 v73, v231, v73, s[34:35]
	v_cndmask_b32_e64 v74, v231, v74, s[100:101]
	v_cndmask_b32_e32 v75, v231, v75, vcc
	v_max3_f32 v200, v56, s10, v57
	v_max3_f32 v200, v200, v58, v59
	v_max3_f32 v200, v200, v72, v73
	v_max3_f32 v200, v200, v74, v75
	v_max3_f32 v200, v200, v88, v89
	v_max3_f32 v200, v200, v90, v91
	v_max3_f32 v200, v200, v84, v85
	v_max3_f32 v200, v200, v86, v87
	v_max3_f32 v200, v200, v80, v81
	v_max3_f32 v200, v200, v82, v83
	v_max3_f32 v200, v200, v76, v77
	v_max3_f32 v200, v200, v78, v79
	v_max3_f32 v200, v200, v64, v65
	v_max3_f32 v200, v200, v66, v67
	v_max3_f32 v200, v200, v68, v69
	v_max3_f32 v200, v200, v70, v71
	v_cmp_le_u32_e64 s[46:47], v172, v97
	v_cmp_le_u32_e64 s[34:35], v173, v97
	v_cmp_le_u32_e64 s[100:101], v175, v97
	v_cmp_le_u32_e32 vcc, v177, v97
	v_cndmask_b32_e64 v60, v231, v60, s[46:47]
	v_cndmask_b32_e64 v201, v231, v61, s[34:35]
	v_cndmask_b32_e32 v202, v231, v63, vcc
	v_max3_f32 v61, v200, v60, v201
	v_cndmask_b32_e64 v200, v231, v62, s[100:101]
	v_cmp_le_u32_e64 s[46:47], v191, v97
	v_cmp_le_u32_e64 s[34:35], v192, v97
	v_cmp_le_u32_e64 s[100:101], v194, v97
	v_cmp_le_u32_e32 vcc, v196, v97
	v_cndmask_b32_e64 v203, v231, v52, s[46:47]
	v_cndmask_b32_e64 v204, v231, v53, s[34:35]
	v_cndmask_b32_e64 v205, v231, v54, s[100:101]
	v_cndmask_b32_e32 v55, v231, v55, vcc
	v_max3_f32 v61, v61, v200, v202
	v_max3_f32 v52, v61, v203, v204
	v_and_b32_e32 v53, 64, v226
	v_max3_f32 v2, v52, v205, v55
	s_branch .Lattn_mask_join

.LBB0_1139:
	v_cmp_gt_f32_e32 vcc, s19, v3
	s_mov_b32 s10, 0x3f317217
	v_readlane_b32 s64, v252, 16
	v_cndmask_b32_e64 v68, 0, 32, vcc
	v_ldexp_f32 v68, v3, v68
	v_log_f32_e32 v68, v68
	v_readlane_b32 s66, v252, 18
	v_readlane_b32 s67, v252, 19
	v_readlane_b32 s65, v252, 17
	v_mul_f32_e32 v69, 0x3f317217, v68
	v_fma_f32 v69, v68, s10, -v69
	v_fmac_f32_e32 v69, 0x3377d1cf, v68
	s_mov_b32 s10, 0x7f800000
	v_fmac_f32_e32 v69, 0x3f317217, v68
	v_cmp_lt_f32_e64 s[46:47], |v68|, s10
	s_mov_b32 s10, 0x23c00000
	v_readlane_b32 s68, v252, 20
	v_cndmask_b32_e64 v68, v68, v69, s[46:47]
	v_cndmask_b32_e32 v69, 0, v228, vcc
	v_sub_f32_e32 v68, v68, v69
	v_add_f32_e32 v2, v2, v68
	v_readlane_b32 s69, v252, 21
	v_readlane_b32 s70, v252, 22
	v_readlane_b32 s71, v252, 23
	v_readlane_b32 s72, v252, 24
	v_readlane_b32 s73, v252, 25
	v_readlane_b32 s74, v252, 26
	v_readlane_b32 s75, v252, 27
	v_readlane_b32 s76, v252, 28
	v_readlane_b32 s77, v252, 29
	v_readlane_b32 s78, v252, 30
	v_readlane_b32 s79, v252, 31
	s_waitcnt vmcnt(0)
	v_sub_f32_e32 v2, v241, v2
	v_mul_f32_e32 v2, 0x3fb8aa3b, v2
	v_exp_f32_e32 v2, v2
	s_nop 0
	v_add_f32_e32 v2, 1.0, v2
	s_nop 0
	v_rcp_f32_e32 v2, v2
	s_nop 0
	v_div_scale_f32 v68, s[34:35], v3, v3, v2
	v_rcp_f32_e32 v69, v68
	s_mov_b64 s[34:35], 0x23c00c00
	v_fma_f32 v71, -v68, v69, 1.0
	v_fmac_f32_e32 v69, v71, v69
	v_div_scale_f32 v71, vcc, v2, v3, v2
	v_mul_f32_e32 v74, v71, v69
	v_fma_f32 v75, -v68, v74, v71
	v_fmac_f32_e32 v74, v75, v69
	v_fma_f32 v68, -v68, v74, v71
	v_div_fmas_f32 v68, v68, v69, v74
	v_div_fixup_f32 v68, v68, v3, v2
	v_lshlrev_b64 v[2:3], 12, v[72:73]
	v_mov_b32_e32 v73, v66
	v_mov_b32_e32 v66, v65
	v_mov_b32_e32 v72, v64
	v_pk_mul_f32 v[64:65], v[66:67], v[68:69] op_sel_hi:[1,0]
	v_lshl_add_u64 v[2:3], s[0:1], 0, v[2:3]
	v_pk_mul_f32 v[72:73], v[72:73], v[68:69] op_sel_hi:[1,0]
	v_and_b32_sdwa v69, v64, v225 dst_sel:DWORD dst_unused:UNUSED_PAD src0_sel:WORD_1 src1_sel:DWORD
	v_lshl_add_u64 v[2:3], v[2:3], 0, v[0:1]
	v_mov_b32_e32 v71, v1
	v_and_b32_sdwa v66, v72, v225 dst_sel:DWORD dst_unused:UNUSED_PAD src0_sel:WORD_1 src1_sel:DWORD
	v_add3_u32 v64, v64, v69, s23
	v_lshl_add_u64 v[70:71], v[2:3], 0, v[70:71]
	v_add3_u32 v66, v72, v66, s23
	v_and_b32_e32 v64, 0xffff0000, v64
	v_or_b32_sdwa v64, v64, v66 dst_sel:DWORD dst_unused:UNUSED_PAD src0_sel:DWORD src1_sel:WORD_1
	v_add_co_u32_e32 v66, vcc, s10, v70
	v_cvt_pk_bf16_f32 v65, v73, v65
	s_nop 0
	v_addc_co_u32_e32 v67, vcc, 0, v71, vcc
	global_store_dwordx2 v[66:67], v[64:65], off offset:3072 nt
	v_mov_b32_e32 v64, v60
	v_mov_b32_e32 v65, v62
	v_pk_mul_f32 v[64:65], v[64:65], v[68:69] op_sel_hi:[1,0]
	v_mov_b32_e32 v62, v61
	v_pk_mul_f32 v[60:61], v[62:63], v[68:69] op_sel_hi:[1,0]
	v_and_b32_sdwa v62, v64, v225 dst_sel:DWORD dst_unused:UNUSED_PAD src0_sel:WORD_1 src1_sel:DWORD
	v_add3_u32 v62, v64, v62, s23
	v_and_b32_sdwa v64, v60, v225 dst_sel:DWORD dst_unused:UNUSED_PAD src0_sel:WORD_1 src1_sel:DWORD
	v_add3_u32 v60, v60, v64, s23
	v_and_b32_e32 v60, 0xffff0000, v60
	v_lshl_add_u64 v[2:3], v[70:71], 0, s[34:35]
	v_cvt_pk_bf16_f32 v61, v65, v61
	v_or_b32_sdwa v60, v60, v62 dst_sel:DWORD dst_unused:UNUSED_PAD src0_sel:DWORD src1_sel:WORD_1
	global_store_dwordx2 v[2:3], v[60:61], off offset:32 nt
	v_mov_b32_e32 v60, v56
	v_mov_b32_e32 v61, v58
	v_pk_mul_f32 v[60:61], v[60:61], v[68:69] op_sel_hi:[1,0]
	v_mov_b32_e32 v58, v57
	v_pk_mul_f32 v[56:57], v[58:59], v[68:69] op_sel_hi:[1,0]
	v_and_b32_sdwa v58, v60, v225 dst_sel:DWORD dst_unused:UNUSED_PAD src0_sel:WORD_1 src1_sel:DWORD
	v_add3_u32 v58, v60, v58, s23
	v_and_b32_sdwa v60, v56, v225 dst_sel:DWORD dst_unused:UNUSED_PAD src0_sel:WORD_1 src1_sel:DWORD
	v_add3_u32 v56, v56, v60, s23
	v_and_b32_e32 v56, 0xffff0000, v56
	v_cvt_pk_bf16_f32 v57, v61, v57
	v_or_b32_sdwa v56, v56, v58 dst_sel:DWORD dst_unused:UNUSED_PAD src0_sel:DWORD src1_sel:WORD_1
	global_store_dwordx2 v[2:3], v[56:57], off offset:64 nt
	v_mov_b32_e32 v56, v52
	v_mov_b32_e32 v57, v54
	v_pk_mul_f32 v[56:57], v[56:57], v[68:69] op_sel_hi:[1,0]
	v_mov_b32_e32 v54, v53
	v_pk_mul_f32 v[52:53], v[54:55], v[68:69] op_sel_hi:[1,0]
	v_and_b32_sdwa v54, v56, v225 dst_sel:DWORD dst_unused:UNUSED_PAD src0_sel:WORD_1 src1_sel:DWORD
	v_add3_u32 v54, v56, v54, s23
	v_and_b32_sdwa v56, v52, v225 dst_sel:DWORD dst_unused:UNUSED_PAD src0_sel:WORD_1 src1_sel:DWORD
	v_add3_u32 v52, v52, v56, s23
	v_and_b32_e32 v52, 0xffff0000, v52
	v_cvt_pk_bf16_f32 v53, v57, v53
	v_or_b32_sdwa v52, v52, v54 dst_sel:DWORD dst_unused:UNUSED_PAD src0_sel:DWORD src1_sel:WORD_1
	global_store_dwordx2 v[2:3], v[52:53], off offset:96 nt
	s_or_b64 exec, exec, s[58:59]
	s_xor_b32 s10, s11, 1
	s_and_saveexec_b64 s[46:47], s[44:45]
	s_cbranch_execz .LBB0_1120
